# phase6 GEMM: A via LDS-DMA full-line pair slots, B unpadded swizzled LDS, saddr loads
# speedup vs baseline: 1.0295x; 1.0295x over previous
.LBB0_1355:
	s_or_b64 exec, exec, s[4:5]
	s_movk_i32 s12, 0xc0
	v_readlane_b32 s0, v245, 13
	s_barrier
	s_cmp_ge_i32 s0, s12
	s_cbranch_scc1 .LBB0_1366
	v_mov_b32_e32 v20, v187
	v_readlane_b32 s4, v245, 5
	v_readlane_b32 s5, v245, 6
	s_lshl_b32 s0, s85, 27
	v_lshrrev_b32_e32 v2, 3, v20
	v_and_b32_e32 v2, 7, v2
	v_and_b32_e32 v3, 0xc0, v20
	v_or_b32_e32 v178, v2, v3
	v_mov_b32_e32 v179, v1
	v_lshl_add_u64 v[2:3], v[178:179], 2, s[4:5]
	global_load_dword v162, v[2:3], off
	global_load_dword v163, v[2:3], off offset:32
	global_load_dword v164, v[2:3], off offset:64
	global_load_dword v165, v[2:3], off offset:96
	global_load_dword v166, v[2:3], off offset:128
	global_load_dword v167, v[2:3], off offset:160
	global_load_dword v168, v[2:3], off offset:192
	global_load_dword v169, v[2:3], off offset:224
	v_readlane_b32 s48, v247, 45
	v_readlane_b32 s49, v247, 46
	s_add_u32 s13, s48, s0
	s_addc_u32 s34, s49, 0
	v_readlane_b32 s4, v245, 7
	v_readlane_b32 s5, v245, 8
	s_add_u32 s0, s13, s4
	s_addc_u32 s4, s34, s5
	v_readlane_b32 s5, v245, 9
	s_add_u32 s6, s0, s5
	s_addc_u32 s7, s4, 0
	v_lshlrev_b32_e32 v4, 6, v20
	v_lshlrev_b32_e32 v5, 2, v20
	v_ashrrev_i32_e32 v23, 5, v20
	v_and_b32_e32 v4, 0x400, v4
	v_and_b32_e32 v2, 60, v5
	v_lshlrev_b32_e32 v5, 13, v23
	v_or3_b32 v190, v4, v5, v2
	v_mov_b32_e32 v191, v1
	v_lshlrev_b32_e32 v192, 2, v190
	s_movk_i32 s14, 0x4000
	v_bfe_u32 v197, v20, 5, 1
	v_and_b32_e32 v218, 0xffffffc0, v20
	v_lshlrev_b32_e32 v198, 1, v2
	v_and_b32_e32 v3, 31, v20
	v_cmp_gt_u32_e64 s[4:5], 16, v3
	v_cndmask_b32_e64 v4, 2, 0, s[4:5]
	v_lshlrev_b32_e32 v200, 1, v4
	v_readlane_b32 s35, v245, 16
	v_readlane_b32 s37, v245, 13
	v_readfirstlane_b32 s53, v20
	s_and_b32 s53, s53, 0xc0
	s_lshl_b32 s53, s53, 8
	s_movk_i32 s54, 0x2000
	s_add_u32 s56, s22, 0xfffff000
	s_addc_u32 s57, s23, -1
	v_lshrrev_b32_e32 v4, 1, v3
	v_and_b32_e32 v4, 7, v4
	v_xor_b32_e32 v4, v4, v197
	v_lshlrev_b32_e32 v4, 4, v4
	v_lshl_or_b32 v4, v3, 7, v4
	v_or_b32_e32 v216, s53, v4
	v_xor_b32_e32 v0, 32, v216
	v_xor_b32_e32 v180, 64, v216
	v_xor_b32_e32 v194, 0x60, v216
	v_lshrrev_b32_e32 v4, 2, v3
	v_and_b32_e32 v4, 3, v4
	v_xor_b32_e32 v5, v4, v197
	v_lshlrev_b32_e32 v5, 4, v5
	v_lshl_or_b32 v5, v3, 6, v5
	v_add_u32_e32 v217, 0x10000, v5
	v_xor_b32_e32 v209, 32, v217
	v_lshrrev_b32_e32 v5, 1, v23
	v_xor_b32_e32 v5, v5, v4
	v_lshlrev_b32_e32 v5, 4, v5
	v_and_b32_e32 v6, 1, v23
	v_lshl_or_b32 v5, v6, 3, v5
	v_lshl_or_b32 v5, v3, 6, v5
	v_add_u32_e32 v219, 0x10000, v5
	v_and_b32_e32 v4, 7, v20
	v_bfe_u32 v5, v20, 4, 2
	v_xor_b32_e32 v4, v4, v5
	v_lshlrev_b32_e32 v196, 4, v4
	v_xor_b32_e32 v215, 64, v196
	s_waitcnt vmcnt(0)
	v_lshl_add_u32 v162, v162, 11, v196
	v_lshl_add_u32 v163, v163, 11, v215
	v_lshl_add_u32 v164, v164, 11, v196
	v_lshl_add_u32 v165, v165, 11, v215
	v_lshl_add_u32 v166, v166, 11, v196
	v_lshl_add_u32 v167, v167, 11, v215
	v_lshl_add_u32 v168, v168, 11, v196
	v_lshl_add_u32 v169, v169, 11, v215
	v_add_u32_e32 v162, 0x1000, v162
	v_add_u32_e32 v163, 0xc00, v163
	v_add_u32_e32 v164, 0x800, v164
	v_add_u32_e32 v165, 0x400, v165
	v_add_u32_e32 v166, 0x1000, v166
	v_add_u32_e32 v167, 0xc00, v167
	v_add_u32_e32 v168, 0x800, v168
	v_add_u32_e32 v169, 0x400, v169
	s_lshl_b32 s0, s35, 1
	s_add_i32 s0, s0, 0
	s_and_b32 s40, s0, 30
	s_lshl_b32 s40, s40, 6
	s_add_u32 s40, s56, s40
	s_addc_u32 s41, s57, 0
	s_and_b32 s58, s0, 31
	s_lshl_b32 s58, s58, 18
	s_add_u32 s58, s6, s58
	s_addc_u32 s59, s7, 0
	s_add_u32 s60, s58, s33
	s_addc_u32 s61, s59, 0
	s_add_u32 s62, s58, s14
	s_addc_u32 s63, s59, 0
	s_add_u32 s64, s58, s97
	s_addc_u32 s65, s59, 0
	s_mov_b32 m0, s53
	s_nop 0
	global_load_lds_dwordx4 v162, s[40:41]
	global_load_lds_dwordx4 v163, s[40:41] offset:1024
	global_load_lds_dwordx4 v164, s[40:41] offset:2048
	global_load_lds_dwordx4 v165, s[40:41] offset:3072
	s_add_u32 m0, m0, 0x1000
	s_nop 0
	global_load_lds_dwordx4 v166, s[40:41]
	global_load_lds_dwordx4 v167, s[40:41] offset:1024
	global_load_lds_dwordx4 v168, s[40:41] offset:2048
	global_load_lds_dwordx4 v169, s[40:41] offset:3072
	global_load_dwordx4 v[130:133], v192, s[58:59]
	global_load_dwordx4 v[134:137], v192, s[60:61]
	global_load_dwordx4 v[138:141], v192, s[62:63]
	global_load_dwordx4 v[142:145], v192, s[64:65]
	s_add_i32 s0, s0, 1
	s_and_b32 s58, s0, 31
	s_lshl_b32 s58, s58, 18
	s_add_u32 s58, s6, s58
	s_addc_u32 s59, s7, 0
	s_add_u32 s60, s58, s33
	s_addc_u32 s61, s59, 0
	s_add_u32 s62, s58, s14
	s_addc_u32 s63, s59, 0
	s_add_u32 s64, s58, s97
	s_addc_u32 s65, s59, 0
	global_load_dwordx4 v[146:149], v192, s[58:59]
	global_load_dwordx4 v[150:153], v192, s[60:61]
	global_load_dwordx4 v[154:157], v192, s[62:63]
	global_load_dwordx4 v[158:161], v192, s[64:65]
	s_branch .LBB0_1358

.LBB0_1358:
	s_add_i32 s36, s37, s86
	s_cmp_ge_i32 s36, s12
	s_cselect_b64 s[8:9], -1, 0
	s_and_b64 vcc, exec, s[8:9]
	s_mov_b64 s[10:11], s[6:7]
	v_mov_b32_e32 v170, v162
	v_mov_b32_e32 v171, v163
	v_mov_b32_e32 v172, v164
	v_mov_b32_e32 v173, v165
	v_mov_b32_e32 v174, v166
	v_mov_b32_e32 v175, v167
	v_mov_b32_e32 v176, v168
	v_mov_b32_e32 v177, v169
	s_mov_b32 s38, s35
	s_cbranch_vccnz .LBB0_1360
	s_mul_hi_u32 s40, s36, 0xaaaaaaab
	s_lshr_b32 s0, s40, 6
	v_readlane_b32 s10, v245, 12
	s_add_i32 s10, s0, s10
	s_mulk_i32 s0, 0x60
	s_sub_i32 s0, s36, s0
	s_mul_i32 s11, s0, 0xab
	s_bfe_u32 s41, s11, 0x6000a
	s_mul_i32 s11, s41, 6
	s_sub_i32 s11, s0, s11
	s_mul_i32 s0, s10, 0x600
	s_lshl_b64 s[38:39], s[0:1], 2
	s_add_u32 s0, s16, s38
	s_addc_u32 s39, s17, s39
	s_and_b32 s11, s11, 0xff
	s_lshl_b32 s11, s11, 10
	s_add_u32 s38, s0, s11
	s_addc_u32 s39, s39, 0
	v_lshl_add_u64 v[2:3], v[178:179], 2, s[38:39]
	global_load_dword v170, v[2:3], off
	global_load_dword v171, v[2:3], off offset:32
	global_load_dword v172, v[2:3], off offset:64
	global_load_dword v173, v[2:3], off offset:96
	global_load_dword v174, v[2:3], off offset:128
	global_load_dword v175, v[2:3], off offset:160
	global_load_dword v176, v[2:3], off offset:192
	global_load_dword v177, v[2:3], off offset:224
	s_mov_b32 s11, s1
	s_lshl_b64 s[10:11], s[10:11], 23
	s_add_u32 s0, s13, s10
	s_addc_u32 s11, s34, s11
	s_lshl_b32 s10, s41, 8
	s_add_u32 s10, s0, s10
	s_addc_u32 s11, s11, 0
	s_lshr_b32 s0, s40, 2
	s_mul_i32 s0, s0, 6
	s_bfe_u32 s38, s40, 0x10002
	s_sub_i32 s0, s36, s0
	s_add_i32 s38, s38, s0
	s_waitcnt vmcnt(0)
	v_lshl_add_u32 v170, v170, 11, v196
	v_lshl_add_u32 v171, v171, 11, v215
	v_lshl_add_u32 v172, v172, 11, v196
	v_lshl_add_u32 v173, v173, 11, v215
	v_lshl_add_u32 v174, v174, 11, v196
	v_lshl_add_u32 v175, v175, 11, v215
	v_lshl_add_u32 v176, v176, 11, v196
	v_lshl_add_u32 v177, v177, 11, v215
	v_add_u32_e32 v170, 0x1000, v170
	v_add_u32_e32 v171, 0xc00, v171
	v_add_u32_e32 v172, 0x800, v172
	v_add_u32_e32 v173, 0x400, v173
	v_add_u32_e32 v174, 0x1000, v174
	v_add_u32_e32 v175, 0xc00, v175
	v_add_u32_e32 v176, 0x800, v176
	v_add_u32_e32 v177, 0x400, v177
.LBB0_1360:
	v_mov_b32_e32 v2, 0
	s_mov_b32 s39, 0
	s_mov_b32 s52, 2
	v_mov_b32_e32 v3, v2
	v_mov_b32_e32 v4, v2
	v_mov_b32_e32 v5, v2
	v_mov_b32_e32 v6, v2
	v_mov_b32_e32 v7, v2
	v_mov_b32_e32 v8, v2
	v_mov_b32_e32 v9, v2
	v_mov_b32_e32 v10, v2
	v_mov_b32_e32 v11, v2
	v_mov_b32_e32 v12, v2
	v_mov_b32_e32 v13, v2
	v_mov_b32_e32 v14, v2
	v_mov_b32_e32 v15, v2
	v_mov_b32_e32 v16, v2
	v_mov_b32_e32 v17, v2
	v_mov_b32_e32 v18, v2
	v_mov_b32_e32 v19, v2
	v_mov_b32_e32 v20, v2
	v_mov_b32_e32 v21, v2
	v_mov_b32_e32 v22, v2
	v_mov_b32_e32 v23, v2
	v_mov_b32_e32 v24, v2
	v_mov_b32_e32 v25, v2
	v_mov_b32_e32 v26, v2
	v_mov_b32_e32 v27, v2
	v_mov_b32_e32 v28, v2
	v_mov_b32_e32 v29, v2
	v_mov_b32_e32 v30, v2
	v_mov_b32_e32 v31, v2
	v_mov_b32_e32 v32, v2
	v_mov_b32_e32 v33, v2
	v_mov_b32_e32 v34, v2
	v_mov_b32_e32 v35, v2
	v_mov_b32_e32 v36, v2
	v_mov_b32_e32 v37, v2
	v_mov_b32_e32 v38, v2
	v_mov_b32_e32 v39, v2
	v_mov_b32_e32 v40, v2
	v_mov_b32_e32 v41, v2
	v_mov_b32_e32 v42, v2
	v_mov_b32_e32 v43, v2
	v_mov_b32_e32 v44, v2
	v_mov_b32_e32 v45, v2
	v_mov_b32_e32 v46, v2
	v_mov_b32_e32 v47, v2
	v_mov_b32_e32 v48, v2
	v_mov_b32_e32 v49, v2
	v_mov_b32_e32 v50, v2
	v_mov_b32_e32 v51, v2
	v_mov_b32_e32 v52, v2
	v_mov_b32_e32 v53, v2
	v_mov_b32_e32 v54, v2
	v_mov_b32_e32 v55, v2
	v_mov_b32_e32 v56, v2
	v_mov_b32_e32 v57, v2
	v_mov_b32_e32 v58, v2
	v_mov_b32_e32 v59, v2
	v_mov_b32_e32 v60, v2
	v_mov_b32_e32 v61, v2
	v_mov_b32_e32 v62, v2
	v_mov_b32_e32 v63, v2
	v_mov_b32_e32 v64, v2
	v_mov_b32_e32 v65, v2
	v_mov_b32_e32 v66, v2
	v_mov_b32_e32 v67, v2
	v_mov_b32_e32 v68, v2
	v_mov_b32_e32 v69, v2
	v_mov_b32_e32 v70, v2
	v_mov_b32_e32 v71, v2
	v_mov_b32_e32 v72, v2
	v_mov_b32_e32 v73, v2
	v_mov_b32_e32 v74, v2
	v_mov_b32_e32 v75, v2
	v_mov_b32_e32 v76, v2
	v_mov_b32_e32 v77, v2
	v_mov_b32_e32 v78, v2
	v_mov_b32_e32 v79, v2
	v_mov_b32_e32 v80, v2
	v_mov_b32_e32 v81, v2
	v_mov_b32_e32 v82, v2
	v_mov_b32_e32 v83, v2
	v_mov_b32_e32 v84, v2
	v_mov_b32_e32 v85, v2
	v_mov_b32_e32 v86, v2
	v_mov_b32_e32 v87, v2
	v_mov_b32_e32 v88, v2
	v_mov_b32_e32 v89, v2
	v_mov_b32_e32 v90, v2
	v_mov_b32_e32 v91, v2
	v_mov_b32_e32 v92, v2
	v_mov_b32_e32 v93, v2
	v_mov_b32_e32 v94, v2
	v_mov_b32_e32 v95, v2
	v_mov_b32_e32 v96, v2
	v_mov_b32_e32 v97, v2
	v_mov_b32_e32 v98, v2
	v_mov_b32_e32 v99, v2
	v_mov_b32_e32 v100, v2
	v_mov_b32_e32 v101, v2
	v_mov_b32_e32 v102, v2
	v_mov_b32_e32 v103, v2
	v_mov_b32_e32 v104, v2
	v_mov_b32_e32 v105, v2
	v_mov_b32_e32 v106, v2
	v_mov_b32_e32 v107, v2
	v_mov_b32_e32 v108, v2
	v_mov_b32_e32 v109, v2
	v_mov_b32_e32 v110, v2
	v_mov_b32_e32 v111, v2
	v_mov_b32_e32 v112, v2
	v_mov_b32_e32 v113, v2
	v_mov_b32_e32 v114, v2
	v_mov_b32_e32 v115, v2
	v_mov_b32_e32 v116, v2
	v_mov_b32_e32 v117, v2
	v_mov_b32_e32 v118, v2
	v_mov_b32_e32 v119, v2
	v_mov_b32_e32 v120, v2
	v_mov_b32_e32 v121, v2
	v_mov_b32_e32 v122, v2
	v_mov_b32_e32 v123, v2
	v_mov_b32_e32 v124, v2
	v_mov_b32_e32 v125, v2
	v_mov_b32_e32 v126, v2
	v_mov_b32_e32 v127, v2
	v_mov_b32_e32 v128, v2
	v_mov_b32_e32 v129, v2
	s_branch .Lg6_loop
.Lg6_switch:
	v_mov_b32_e32 v162, v170
	v_mov_b32_e32 v163, v171
	v_mov_b32_e32 v164, v172
	v_mov_b32_e32 v165, v173
	v_mov_b32_e32 v166, v174
	v_mov_b32_e32 v167, v175
	v_mov_b32_e32 v168, v176
	v_mov_b32_e32 v169, v177
	s_mov_b64 s[6:7], s[10:11]
	s_mov_b32 s35, s38
	s_mov_b32 s52, 0
	s_branch .Lg6_noswitch
.Lg6_loop:
	s_cmp_eq_u32 s39, 15
	s_cbranch_scc1 .Lg6_switch
.Lg6_noswitch:
	s_waitcnt vmcnt(4)
	v_cvt_pk_bf16_f32 v202, v130, v134
	v_cvt_pk_bf16_f32 v203, v138, v142
	v_cvt_pk_bf16_f32 v204, v131, v135
	v_cvt_pk_bf16_f32 v205, v139, v143
	ds_write2st64_b64 v219, v[202:203], v[204:205] offset0:0 offset1:4
	v_cvt_pk_bf16_f32 v206, v132, v136
	v_cvt_pk_bf16_f32 v207, v140, v144
	v_cvt_pk_bf16_f32 v202, v133, v137
	v_cvt_pk_bf16_f32 v203, v141, v145
	ds_write2st64_b64 v219, v[206:207], v[202:203] offset0:8 offset1:12
	s_waitcnt lgkmcnt(0)
	s_barrier
	s_lshl_b32 s0, s35, 1
	s_add_i32 s0, s0, s52
	s_and_b32 s40, s0, 30
	s_lshl_b32 s40, s40, 6
	s_add_u32 s40, s56, s40
	s_addc_u32 s41, s57, 0
	s_and_b32 s58, s0, 31
	s_lshl_b32 s58, s58, 18
	s_add_u32 s58, s6, s58
	s_addc_u32 s59, s7, 0
	s_add_u32 s60, s58, s33
	s_addc_u32 s61, s59, 0
	s_add_u32 s62, s58, s14
	s_addc_u32 s63, s59, 0
	s_add_u32 s64, s58, s97
	s_addc_u32 s65, s59, 0
	s_add_i32 s32, s53, s54
	s_mov_b32 m0, s32
	ds_read_b128 v[220:223], v216
	ds_read_b128 v[224:227], v216 offset:4096
	ds_read_b128 v[228:231], v217
	ds_read_b128 v[232:235], v217 offset:2048
	ds_read_b128 v[236:239], v217 offset:4096
	ds_read_b128 v[240:243], v217 offset:6144
	s_waitcnt lgkmcnt(3)
	v_mfma_f32_32x32x16_bf16 v[114:129], v[220:223], v[228:231], v[114:129]
	global_load_lds_dwordx4 v162, s[40:41]
	s_waitcnt lgkmcnt(2)
	v_mfma_f32_32x32x16_bf16 v[98:113], v[220:223], v[232:235], v[98:113]
	global_load_lds_dwordx4 v163, s[40:41] offset:1024
	s_waitcnt lgkmcnt(1)
	v_mfma_f32_32x32x16_bf16 v[82:97], v[220:223], v[236:239], v[82:97]
	global_load_lds_dwordx4 v164, s[40:41] offset:2048
	s_waitcnt lgkmcnt(0)
	v_mfma_f32_32x32x16_bf16 v[66:81], v[220:223], v[240:243], v[66:81]
	global_load_lds_dwordx4 v165, s[40:41] offset:3072
	s_add_u32 m0, m0, 0x1000
	v_mfma_f32_32x32x16_bf16 v[50:65], v[224:227], v[228:231], v[50:65]
	global_load_lds_dwordx4 v166, s[40:41]
	v_mfma_f32_32x32x16_bf16 v[34:49], v[224:227], v[232:235], v[34:49]
	global_load_lds_dwordx4 v167, s[40:41] offset:1024
	v_mfma_f32_32x32x16_bf16 v[18:33], v[224:227], v[236:239], v[18:33]
	global_load_lds_dwordx4 v168, s[40:41] offset:2048
	v_mfma_f32_32x32x16_bf16 v[2:17], v[224:227], v[240:243], v[2:17]
	global_load_lds_dwordx4 v169, s[40:41] offset:3072
	ds_read_b128 v[220:223], v0
	ds_read_b128 v[224:227], v0 offset:4096
	ds_read_b128 v[228:231], v209
	ds_read_b128 v[232:235], v209 offset:2048
	ds_read_b128 v[236:239], v209 offset:4096
	ds_read_b128 v[240:243], v209 offset:6144
	s_waitcnt lgkmcnt(3)
	v_mfma_f32_32x32x16_bf16 v[114:129], v[220:223], v[228:231], v[114:129]
	global_load_dwordx4 v[130:133], v192, s[58:59]
	s_waitcnt lgkmcnt(2)
	v_mfma_f32_32x32x16_bf16 v[98:113], v[220:223], v[232:235], v[98:113]
	global_load_dwordx4 v[134:137], v192, s[60:61]
	s_waitcnt lgkmcnt(1)
	v_mfma_f32_32x32x16_bf16 v[82:97], v[220:223], v[236:239], v[82:97]
	global_load_dwordx4 v[138:141], v192, s[62:63]
	s_waitcnt lgkmcnt(0)
	v_mfma_f32_32x32x16_bf16 v[66:81], v[220:223], v[240:243], v[66:81]
	global_load_dwordx4 v[142:145], v192, s[64:65]
	v_mfma_f32_32x32x16_bf16 v[50:65], v[224:227], v[228:231], v[50:65]
	v_mfma_f32_32x32x16_bf16 v[34:49], v[224:227], v[232:235], v[34:49]
	v_mfma_f32_32x32x16_bf16 v[18:33], v[224:227], v[236:239], v[18:33]
	v_mfma_f32_32x32x16_bf16 v[2:17], v[224:227], v[240:243], v[2:17]
	s_waitcnt vmcnt(12)
	v_cvt_pk_bf16_f32 v202, v146, v150
	v_cvt_pk_bf16_f32 v203, v154, v158
	v_cvt_pk_bf16_f32 v204, v147, v151
	v_cvt_pk_bf16_f32 v205, v155, v159
	ds_write2st64_b64 v219, v[202:203], v[204:205] offset0:16 offset1:20
	v_cvt_pk_bf16_f32 v206, v148, v152
	v_cvt_pk_bf16_f32 v207, v156, v160
	v_cvt_pk_bf16_f32 v202, v149, v153
	v_cvt_pk_bf16_f32 v203, v157, v161
	ds_write2st64_b64 v219, v[206:207], v[202:203] offset0:24 offset1:28
	s_waitcnt lgkmcnt(0)
	s_barrier
	s_add_i32 s0, s0, 1
	s_and_b32 s58, s0, 31
	s_lshl_b32 s58, s58, 18
	s_add_u32 s58, s6, s58
	s_addc_u32 s59, s7, 0
	s_add_u32 s60, s58, s33
	s_addc_u32 s61, s59, 0
	s_add_u32 s62, s58, s14
	s_addc_u32 s63, s59, 0
	s_add_u32 s64, s58, s97
	s_addc_u32 s65, s59, 0
	ds_read_b128 v[220:223], v180
	ds_read_b128 v[224:227], v180 offset:4096
	ds_read_b128 v[228:231], v217 offset:8192
	ds_read_b128 v[232:235], v217 offset:10240
	ds_read_b128 v[236:239], v217 offset:12288
	ds_read_b128 v[240:243], v217 offset:14336
	s_waitcnt lgkmcnt(3)
	v_mfma_f32_32x32x16_bf16 v[114:129], v[220:223], v[228:231], v[114:129]
	global_load_dwordx4 v[146:149], v192, s[58:59]
	s_waitcnt lgkmcnt(2)
	v_mfma_f32_32x32x16_bf16 v[98:113], v[220:223], v[232:235], v[98:113]
	global_load_dwordx4 v[150:153], v192, s[60:61]
	s_waitcnt lgkmcnt(1)
	v_mfma_f32_32x32x16_bf16 v[82:97], v[220:223], v[236:239], v[82:97]
	global_load_dwordx4 v[154:157], v192, s[62:63]
	s_waitcnt lgkmcnt(0)
	v_mfma_f32_32x32x16_bf16 v[66:81], v[220:223], v[240:243], v[66:81]
	global_load_dwordx4 v[158:161], v192, s[64:65]
	v_mfma_f32_32x32x16_bf16 v[50:65], v[224:227], v[228:231], v[50:65]
	v_mfma_f32_32x32x16_bf16 v[34:49], v[224:227], v[232:235], v[34:49]
	v_mfma_f32_32x32x16_bf16 v[18:33], v[224:227], v[236:239], v[18:33]
	v_mfma_f32_32x32x16_bf16 v[2:17], v[224:227], v[240:243], v[2:17]
	ds_read_b128 v[220:223], v194
	ds_read_b128 v[224:227], v194 offset:4096
	ds_read_b128 v[228:231], v209 offset:8192
	ds_read_b128 v[232:235], v209 offset:10240
	ds_read_b128 v[236:239], v209 offset:12288
	ds_read_b128 v[240:243], v209 offset:14336
	s_waitcnt lgkmcnt(3)
	v_mfma_f32_32x32x16_bf16 v[114:129], v[220:223], v[228:231], v[114:129]
	s_waitcnt lgkmcnt(2)
	v_mfma_f32_32x32x16_bf16 v[98:113], v[220:223], v[232:235], v[98:113]
	s_waitcnt lgkmcnt(1)
	v_mfma_f32_32x32x16_bf16 v[82:97], v[220:223], v[236:239], v[82:97]
	s_waitcnt lgkmcnt(0)
	v_mfma_f32_32x32x16_bf16 v[66:81], v[220:223], v[240:243], v[66:81]
	v_mfma_f32_32x32x16_bf16 v[50:65], v[224:227], v[228:231], v[50:65]
	v_mfma_f32_32x32x16_bf16 v[34:49], v[224:227], v[232:235], v[34:49]
	v_mfma_f32_32x32x16_bf16 v[18:33], v[224:227], v[236:239], v[18:33]
	v_mfma_f32_32x32x16_bf16 v[2:17], v[224:227], v[240:243], v[2:17]
	s_xor_b32 s54, s54, 0x2000
	v_xor_b32_e32 v216, 0x2000, v216
	v_xor_b32_e32 v0, 0x2000, v0
	v_xor_b32_e32 v180, 0x2000, v180
	v_xor_b32_e32 v194, 0x2000, v194
	s_add_i32 s52, s52, 2
	s_add_i32 s39, s39, 1
	s_cmp_lt_u32 s39, 16
	s_cbranch_scc1 .Lg6_loop
	s_branch .LBB0_1357

	.amdhsa_kernel _Z4mega6Params
		.amdhsa_group_segment_fixed_size 8192
		.amdhsa_private_segment_fixed_size 0
		.amdhsa_kernarg_size 616
		.amdhsa_user_sgpr_count 2
		.amdhsa_user_sgpr_dispatch_ptr 0
		.amdhsa_user_sgpr_queue_ptr 0
		.amdhsa_user_sgpr_kernarg_segment_ptr 1
		.amdhsa_user_sgpr_dispatch_id 0
		.amdhsa_user_sgpr_kernarg_preload_length 0
		.amdhsa_user_sgpr_kernarg_preload_offset 0
		.amdhsa_user_sgpr_private_segment_size 0
		.amdhsa_uses_dynamic_stack 0
		.amdhsa_enable_private_segment 0
		.amdhsa_system_sgpr_workgroup_id_x 1
		.amdhsa_system_sgpr_workgroup_id_y 0
		.amdhsa_system_sgpr_workgroup_id_z 0
		.amdhsa_system_sgpr_workgroup_info 0
		.amdhsa_system_vgpr_workitem_id 2
		.amdhsa_next_free_vgpr 248
		.amdhsa_next_free_sgpr 100
		.amdhsa_accum_offset 248
		.amdhsa_reserve_vcc 1
		.amdhsa_float_round_mode_32 0
		.amdhsa_float_round_mode_16_64 0
		.amdhsa_float_denorm_mode_32 3
		.amdhsa_float_denorm_mode_16_64 3
		.amdhsa_dx10_clamp 1
		.amdhsa_ieee_mode 1
		.amdhsa_fp16_overflow 0
		.amdhsa_tg_split 0
		.amdhsa_exception_fp_ieee_invalid_op 0
		.amdhsa_exception_fp_denorm_src 0
		.amdhsa_exception_fp_ieee_div_zero 0
		.amdhsa_exception_fp_ieee_overflow 0
		.amdhsa_exception_fp_ieee_underflow 0
		.amdhsa_exception_fp_ieee_inexact 0
		.amdhsa_exception_int_div_zero 0
	.end_amdhsa_kernel

amdhsa.kernels:
  - .agpr_count:     0
    .args:
      - .offset:         0
        .size:           360
        .value_kind:     by_value
      - .offset:         360
        .size:           4
        .value_kind:     hidden_block_count_x
      - .offset:         364
        .size:           4
        .value_kind:     hidden_block_count_y
      - .offset:         368
        .size:           4
        .value_kind:     hidden_block_count_z
      - .offset:         372
        .size:           2
        .value_kind:     hidden_group_size_x
      - .offset:         374
        .size:           2
        .value_kind:     hidden_group_size_y
      - .offset:         376
        .size:           2
        .value_kind:     hidden_group_size_z
      - .offset:         378
        .size:           2
        .value_kind:     hidden_remainder_x
      - .offset:         380
        .size:           2
        .value_kind:     hidden_remainder_y
      - .offset:         382
        .size:           2
        .value_kind:     hidden_remainder_z
      - .offset:         400
        .size:           8
        .value_kind:     hidden_global_offset_x
      - .offset:         408
        .size:           8
        .value_kind:     hidden_global_offset_y
      - .offset:         416
        .size:           8
        .value_kind:     hidden_global_offset_z
      - .offset:         424
        .size:           2
        .value_kind:     hidden_grid_dims
      - .offset:         448
        .size:           8
        .value_kind:     hidden_multigrid_sync_arg
      - .offset:         480
        .size:           4
        .value_kind:     hidden_dynamic_lds_size
    .group_segment_fixed_size: 8192
    .kernarg_segment_align: 8
    .kernarg_segment_size: 616
    .language:       OpenCL C
    .language_version:
      - 2
      - 0
    .max_flat_workgroup_size: 256
    .name:           _Z4mega6Params
    .private_segment_fixed_size: 0
    .sgpr_count:     106
    .sgpr_spill_count: 229
    .symbol:         _Z4mega6Params.kd
    .uniform_work_group_size: 1
    .uses_dynamic_stack: false
    .vgpr_count:     248
    .vgpr_spill_count: 0
    .wavefront_size: 64
